# plus: normaliser scan and state-phase column-sum loops with their loads kept in flight; GLA log-gate loops read both time steps' LDS rows together
# speedup vs baseline: 1.0104x; 1.0056x over previous
; DEVI float logsigf_(float x) { return fminf(x, 0.f) - __logf(1.f + __expf(-fabsf(x))); }
; DEVI void lds_barrier() { asm volatile("s_waitcnt lgkmcnt(0)\n\ts_barrier" ::: "memory"); }
; DEVI float gla_la(const float* gl, int t, const float* w2r, float gb) { float x = gb;
; #pragma unroll
;     for (int r = 0; r < 16; ++r) x += gl[t * 16 + r] * w2r[r];
;     return logsigf_(x) * (1.f / 16.f); }
; template <int KIND>
; DEVI void mix_state_phase(unsigned char* smem, const MixArgs a) {
;     ...
;             for (int t = sg * 32; t < sg * 32 + 32; ++t) ssum += gla_la(gl, t, w2r, gb);
;             seg[sg * 128 + ch] = ssum; lds_barrier();
;             float Bc = 0.f, tot = 0.f;
; #pragma unroll
;             for (int s2 = 0; s2 < 4; ++s2) { const float v = seg[s2 * 128 + ch]; tot += v; if (s2 < sg) Bc += v; }
.LBB0_514:
	v_add_u32_e32 v123, s0, v99
	ds_read_b128 v[124:127], v123
	ds_read_b128 v[128:131], v123 offset:16
	ds_read_b128 v[132:135], v123 offset:32
	ds_read_b128 v[136:139], v123 offset:48
	ds_read_b128 v[176:179], v123 offset:64
	ds_read_b128 v[180:183], v123 offset:80
	ds_read_b128 v[184:187], v123 offset:96
	ds_read_b128 v[188:191], v123 offset:112
	s_addk_i32 s0, 0x80
	s_waitcnt vmcnt(1) lgkmcnt(7)
	v_fma_f32 v140, v119, v124, v8
	v_fmac_f32_e32 v140, v120, v125
	v_fmac_f32_e32 v140, v116, v126
	v_fmac_f32_e32 v140, v121, v127
	s_waitcnt lgkmcnt(6)
	v_fmac_f32_e32 v140, v117, v128
	v_fmac_f32_e32 v140, v118, v129
	v_pk_mul_f32 v[124:125], v[50:51], v[130:131]
	s_cmpk_eq_i32 s0, 0x800
	v_add_f32_e32 v124, v140, v124
	v_add_f32_e32 v126, v124, v125
	s_waitcnt lgkmcnt(5)
	v_pk_mul_f32 v[124:125], v[52:53], v[132:133]
	s_nop 0
	v_add_f32_e32 v124, v126, v124
	v_add_f32_e32 v126, v124, v125
	v_pk_mul_f32 v[124:125], v[88:89], v[134:135]
	s_nop 0
	v_add_f32_e32 v124, v126, v124
	v_add_f32_e32 v126, v124, v125
	s_waitcnt lgkmcnt(4)
	v_pk_mul_f32 v[124:125], v[90:91], v[136:137]
	s_nop 0
	v_add_f32_e32 v124, v126, v124
	v_add_f32_e32 v126, v124, v125
	s_waitcnt vmcnt(0)
	v_pk_mul_f32 v[124:125], v[92:93], v[138:139]
	s_nop 0
	v_add_f32_e32 v124, v126, v124
	v_add_f32_e32 v124, v124, v125
	v_min_f32_e32 v125, 0, v124
	v_mul_f32_e64 v124, |v124|, s73
	v_exp_f32_e32 v124, v124
	s_nop 0
	v_add_f32_e32 v124, 1.0, v124
	v_cmp_gt_f32_e32 vcc, s94, v124
	s_nop 1
	v_cndmask_b32_e64 v126, 0, 32, vcc
	v_ldexp_f32 v124, v124, v126
	v_log_f32_e32 v124, v124
	s_nop 0
	v_mul_f32_e32 v126, 0x3f317217, v124
	v_fma_f32 v126, v124, s97, -v126
	v_fmac_f32_e32 v126, 0x3377d1cf, v124
	v_fmac_f32_e32 v126, 0x3f317217, v124
	v_cmp_lt_f32_e64 s[12:13], |v124|, s23
	s_nop 1
	v_cndmask_b32_e64 v124, v124, v126, s[12:13]
	v_cndmask_b32_e32 v126, 0, v211, vcc
	v_sub_f32_e32 v124, v124, v126
	v_sub_f32_e32 v124, v125, v124
	v_fmac_f32_e32 v122, 0x3d800000, v124
	s_waitcnt lgkmcnt(0)
	v_fma_f32 v128, v119, v176, v8
	v_fmac_f32_e32 v128, v120, v177
	v_fmac_f32_e32 v128, v116, v178
	v_fmac_f32_e32 v128, v121, v179
	v_fmac_f32_e32 v128, v117, v180
	v_fmac_f32_e32 v128, v118, v181
	v_pk_mul_f32 v[124:125], v[50:51], v[182:183]
	s_nop 0
	v_add_f32_e32 v124, v128, v124
	v_add_f32_e32 v128, v124, v125
	v_pk_mul_f32 v[124:125], v[52:53], v[184:185]
	s_nop 0
	v_add_f32_e32 v124, v128, v124
	v_add_f32_e32 v128, v124, v125
	v_pk_mul_f32 v[124:125], v[88:89], v[186:187]
	s_nop 0
	v_add_f32_e32 v124, v128, v124
	v_add_f32_e32 v128, v124, v125
	v_pk_mul_f32 v[124:125], v[90:91], v[188:189]
	s_nop 0
	v_add_f32_e32 v123, v128, v124
	v_add_f32_e32 v123, v123, v125
	v_pk_mul_f32 v[124:125], v[92:93], v[190:191]
	s_nop 0
	v_add_f32_e32 v123, v123, v124
	v_add_f32_e32 v123, v123, v125
	v_min_f32_e32 v124, 0, v123
	v_mul_f32_e64 v123, |v123|, s73
	v_exp_f32_e32 v123, v123
	s_nop 0
	v_add_f32_e32 v123, 1.0, v123
	v_cmp_gt_f32_e32 vcc, s94, v123
	s_nop 1
	v_cndmask_b32_e64 v125, 0, 32, vcc
	v_ldexp_f32 v123, v123, v125
	v_log_f32_e32 v123, v123
	s_nop 0
	v_mul_f32_e32 v125, 0x3f317217, v123
	v_fma_f32 v125, v123, s97, -v125
	v_fmac_f32_e32 v125, 0x3377d1cf, v123
	v_fmac_f32_e32 v125, 0x3f317217, v123
	v_cmp_lt_f32_e64 s[12:13], |v123|, s23
	s_nop 1
	v_cndmask_b32_e64 v123, v123, v125, s[12:13]
	v_cndmask_b32_e32 v125, 0, v211, vcc
	v_sub_f32_e32 v123, v123, v125
	v_sub_f32_e32 v123, v124, v123
	v_fmac_f32_e32 v122, 0x3d800000, v123
	s_cbranch_scc0 .LBB0_514
	ds_write_b32 v95, v122 offset:1536
	s_waitcnt lgkmcnt(0)
	s_barrier
	ds_read2st64_b32 v[122:123], v96 offset0:6 offset1:8
	s_mov_b32 s0, 0
	s_waitcnt lgkmcnt(0)
	v_add_f32_e32 v122, 0, v122
	v_cndmask_b32_e64 v124, 0, v122, s[4:5]
	v_add_f32_e32 v125, v122, v123
	v_add_f32_e32 v122, v123, v124
	v_cndmask_b32_e64 v124, v124, v122, s[6:7]
	ds_read2st64_b32 v[122:123], v96 offset0:10 offset1:12
	s_waitcnt lgkmcnt(0)
	v_add_f32_e32 v125, v125, v122
	v_add_f32_e32 v122, v122, v124
	v_cndmask_b32_e64 v124, v124, v122, s[8:9]
	v_add_f32_e32 v122, v125, v123
	v_add_f32_e32 v123, v123, v124
	v_cndmask_b32_e64 v123, v124, v123, s[10:11]
	v_mov_b32_e32 v124, v100
; DEVI float bf2f(u16 b) { return __uint_as_float(((unsigned)b) << 16); }
; DEVI u16 f2bf(float f) { return (u16)(cvt_pk(f, 0.f) & 0xffffu); }
; template <int KIND>
; DEVI void mix_state_phase(unsigned char* smem, const MixArgs a) {
;     ...
;             for (int t = sg * 32; t < sg * 32 + 32; ++t) { Bc += gla_la(gl, t, w2r, gb);
;                 const float kv = bf2f(KT[t * LP + ch]); KT[t * LP + ch] = f2bf(kv * __expf(tot - Bc)); }
;             if (sg == 0) a.dec[(size_t)item * 128 + ch] = __expf(tot);
.LBB0_516:
	v_add_u32_e32 v125, s0, v99
	ds_read_b128 v[126:129], v125
	ds_read_b128 v[130:133], v125 offset:16
	ds_read_b128 v[134:137], v125 offset:32
	ds_read_b128 v[138:141], v125 offset:48
	ds_read_b128 v[176:179], v125 offset:64
	ds_read_b128 v[180:183], v125 offset:80
	ds_read_b128 v[184:187], v125 offset:96
	ds_read_b128 v[188:191], v125 offset:112
	s_waitcnt lgkmcnt(7)
	v_fma_f32 v142, v119, v126, v8
	v_fmac_f32_e32 v142, v120, v127
	v_fmac_f32_e32 v142, v116, v128
	v_fmac_f32_e32 v142, v121, v129
	s_waitcnt lgkmcnt(6)
	v_fmac_f32_e32 v142, v117, v130
	v_fmac_f32_e32 v142, v118, v131
	v_pk_mul_f32 v[126:127], v[50:51], v[132:133]
	s_nop 0
	v_add_f32_e32 v126, v142, v126
	v_add_f32_e32 v128, v126, v127
	s_waitcnt lgkmcnt(5)
	v_pk_mul_f32 v[126:127], v[52:53], v[134:135]
	s_nop 0
	v_add_f32_e32 v126, v128, v126
	v_add_f32_e32 v128, v126, v127
	v_pk_mul_f32 v[126:127], v[88:89], v[136:137]
	s_nop 0
	v_add_f32_e32 v126, v128, v126
	v_add_f32_e32 v128, v126, v127
	s_waitcnt lgkmcnt(4)
	v_pk_mul_f32 v[126:127], v[90:91], v[138:139]
	s_nop 0
	v_add_f32_e32 v126, v128, v126
	v_add_f32_e32 v128, v126, v127
	v_pk_mul_f32 v[126:127], v[92:93], v[140:141]
	s_nop 0
	v_add_f32_e32 v126, v128, v126
	v_add_f32_e32 v126, v126, v127
	v_min_f32_e32 v127, 0, v126
	v_mul_f32_e64 v126, |v126|, s73
	v_exp_f32_e32 v126, v126
	s_nop 0
	v_add_f32_e32 v126, 1.0, v126
	v_cmp_gt_f32_e32 vcc, s94, v126
	s_nop 1
	v_cndmask_b32_e64 v128, 0, 32, vcc
	v_ldexp_f32 v126, v126, v128
	v_log_f32_e32 v126, v126
	s_nop 0
	v_mul_f32_e32 v128, 0x3f317217, v126
	v_fma_f32 v128, v126, s97, -v128
	v_fmac_f32_e32 v128, 0x3377d1cf, v126
	v_fmac_f32_e32 v128, 0x3f317217, v126
	v_cmp_lt_f32_e64 s[12:13], |v126|, s23
	s_nop 1
	v_cndmask_b32_e64 v126, v126, v128, s[12:13]
	v_cndmask_b32_e32 v128, 0, v211, vcc
	v_sub_f32_e32 v126, v126, v128
	v_sub_f32_e32 v126, v127, v126
	v_fmac_f32_e32 v123, 0x3d800000, v126
	v_add_u32_e32 v126, 0xfffffef0, v124
	ds_read_u16 v127, v126
	v_sub_f32_e32 v128, v122, v123
	v_mul_f32_e32 v128, 0x3fb8aa3b, v128
	v_exp_f32_e32 v128, v128
	s_waitcnt lgkmcnt(0)
	v_lshlrev_b32_e32 v127, 16, v127
	v_mul_f32_e32 v127, v128, v127
	v_cvt_pk_bf16_f32 v127, v127, s0
	ds_write_b16 v126, v127
	s_waitcnt lgkmcnt(0)
	v_fma_f32 v130, v119, v176, v8
	v_fmac_f32_e32 v130, v120, v177
	v_fmac_f32_e32 v130, v116, v178
	v_fmac_f32_e32 v130, v121, v179
	v_fmac_f32_e32 v130, v117, v180
	v_fmac_f32_e32 v130, v118, v181
	v_pk_mul_f32 v[126:127], v[50:51], v[182:183]
	s_nop 0
	v_add_f32_e32 v126, v130, v126
	v_add_f32_e32 v130, v126, v127
	v_pk_mul_f32 v[126:127], v[52:53], v[184:185]
	s_nop 0
	v_add_f32_e32 v126, v130, v126
	v_add_f32_e32 v130, v126, v127
	v_pk_mul_f32 v[126:127], v[88:89], v[186:187]
	s_nop 0
	v_add_f32_e32 v126, v130, v126
	v_add_f32_e32 v130, v126, v127
	v_pk_mul_f32 v[126:127], v[90:91], v[188:189]
	s_nop 0
	v_add_f32_e32 v125, v130, v126
	v_add_f32_e32 v125, v125, v127
	v_pk_mul_f32 v[126:127], v[92:93], v[190:191]
	s_nop 0
	v_add_f32_e32 v125, v125, v126
	v_add_f32_e32 v125, v125, v127
	v_min_f32_e32 v126, 0, v125
	v_mul_f32_e64 v125, |v125|, s73
	v_exp_f32_e32 v125, v125
	s_nop 0
	v_add_f32_e32 v125, 1.0, v125
	v_cmp_gt_f32_e32 vcc, s94, v125
	s_nop 1
	v_cndmask_b32_e64 v127, 0, 32, vcc
	v_ldexp_f32 v125, v125, v127
	v_log_f32_e32 v125, v125
	s_nop 0
	v_mul_f32_e32 v127, 0x3f317217, v125
	v_fma_f32 v127, v125, s97, -v127
	v_fmac_f32_e32 v127, 0x3377d1cf, v125
	v_fmac_f32_e32 v127, 0x3f317217, v125
	v_cmp_lt_f32_e64 s[12:13], |v125|, s23
	s_nop 1
	v_cndmask_b32_e64 v125, v125, v127, s[12:13]
	v_cndmask_b32_e32 v127, 0, v211, vcc
	v_sub_f32_e32 v125, v125, v127
	v_sub_f32_e32 v125, v126, v125
	v_fmac_f32_e32 v123, 0x3d800000, v125
	ds_read_u16 v125, v124
	v_sub_f32_e32 v126, v122, v123
	v_mul_f32_e32 v126, 0x3fb8aa3b, v126
	v_exp_f32_e32 v126, v126
	s_waitcnt lgkmcnt(0)
	v_lshlrev_b32_e32 v125, 16, v125
	v_mul_f32_e32 v125, v126, v125
	v_cvt_pk_bf16_f32 v125, v125, s0
	s_addk_i32 s0, 0x80
	ds_write_b16 v124, v125
	v_add_u32_e32 v124, 0x220, v124
	s_cmpk_eq_i32 s0, 0x800
	s_cbranch_scc0 .LBB0_516
	s_and_saveexec_b64 s[12:13], s[2:3]
	s_cbranch_execz .LBB0_510
	v_mul_f32_e32 v8, 0x3fb8aa3b, v122
	v_exp_f32_e32 v8, v8
	s_lshl_b64 s[0:1], s[14:15], 9
	v_lshl_add_u64 v[50:51], v[80:81], 0, s[0:1]
	global_store_dword v[50:51], v8, off
	s_branch .LBB0_510

; DEVI float bf2f(u16 b) { return __uint_as_float(((unsigned)b) << 16); }
; template <int KIND>
; DEVI void mix_state_phase(unsigned char* smem, const MixArgs a) {
;     ...
;         if (KIND == 0 && tid < 128) { float sum = 0.f; for (int t = 0; t < 128; ++t) sum += bf2f(KT[t * LP + tid]); a.dn[(size_t)item * 128 + tid] = sum; a.dec[(size_t)item * 128 + tid] = __expf(fB[127]); }
.LBB0_570:
	v_add_u32_e32 v10, s0, v133
	v_add_u32_e32 v11, 0x15000, v10
	ds_read_u16 v56, v11
	ds_read_u16 v57, v11 offset:272
	ds_read_u16 v58, v11 offset:544
	ds_read_u16 v59, v11 offset:816
	ds_read_u16 v60, v11 offset:1088
	ds_read_u16 v61, v11 offset:1360
	ds_read_u16 v62, v11 offset:1632
	ds_read_u16 v63, v11 offset:1904
	s_addk_i32 s0, 0x1100
	ds_read_u16 v64, v11 offset:2176
	s_waitcnt lgkmcnt(8)
	v_lshlrev_b32_e32 v56, 16, v56
	v_add_f32_e32 v8, v8, v56
	ds_read_u16 v65, v11 offset:2448
	s_waitcnt lgkmcnt(8)
	v_lshlrev_b32_e32 v57, 16, v57
	v_add_f32_e32 v8, v8, v57
	ds_read_u16 v66, v11 offset:2720
	s_waitcnt lgkmcnt(8)
	v_lshlrev_b32_e32 v58, 16, v58
	v_add_f32_e32 v8, v8, v58
	ds_read_u16 v67, v11 offset:2992
	s_waitcnt lgkmcnt(8)
	v_lshlrev_b32_e32 v59, 16, v59
	v_add_f32_e32 v8, v8, v59
	ds_read_u16 v68, v11 offset:3264
	s_waitcnt lgkmcnt(8)
	v_lshlrev_b32_e32 v60, 16, v60
	v_add_f32_e32 v8, v8, v60
	ds_read_u16 v69, v11 offset:3536
	s_waitcnt lgkmcnt(8)
	v_lshlrev_b32_e32 v61, 16, v61
	v_add_f32_e32 v8, v8, v61
	ds_read_u16 v70, v11 offset:3808
	s_waitcnt lgkmcnt(8)
	v_lshlrev_b32_e32 v62, 16, v62
	v_add_f32_e32 v8, v8, v62
	ds_read_u16 v71, v11 offset:4080
	s_waitcnt lgkmcnt(8)
	v_lshlrev_b32_e32 v63, 16, v63
	v_add_f32_e32 v8, v8, v63
	s_cmpk_eq_u32 s0, 0x8800
	s_waitcnt lgkmcnt(7)
	v_lshlrev_b32_e32 v64, 16, v64
	v_add_f32_e32 v8, v8, v64
	s_waitcnt lgkmcnt(6)
	v_lshlrev_b32_e32 v65, 16, v65
	v_add_f32_e32 v8, v8, v65
	s_waitcnt lgkmcnt(5)
	v_lshlrev_b32_e32 v66, 16, v66
	v_add_f32_e32 v8, v8, v66
	s_waitcnt lgkmcnt(4)
	v_lshlrev_b32_e32 v67, 16, v67
	v_add_f32_e32 v8, v8, v67
	s_waitcnt lgkmcnt(3)
	v_lshlrev_b32_e32 v68, 16, v68
	v_add_f32_e32 v8, v8, v68
	s_waitcnt lgkmcnt(2)
	v_lshlrev_b32_e32 v69, 16, v69
	v_add_f32_e32 v8, v8, v69
	s_waitcnt lgkmcnt(1)
	v_lshlrev_b32_e32 v70, 16, v70
	v_add_f32_e32 v8, v8, v70
	s_waitcnt lgkmcnt(0)
	v_lshlrev_b32_e32 v71, 16, v71
	v_add_f32_e32 v8, v8, v71
	s_cbranch_scc0 .LBB0_570
	s_lshl_b64 s[0:1], s[86:87], 7
	v_lshl_add_u64 v[10:11], s[0:1], 0, v[88:89]
	v_readlane_b32 s0, v252, 46
	v_lshlrev_b64 v[10:11], 2, v[10:11]
	v_readlane_b32 s1, v252, 47
	s_nop 1
	v_lshl_add_u64 v[56:57], s[0:1], 0, v[10:11]
	global_store_dword v[56:57], v8, off
	ds_read_b32 v8, v9 offset:508
	v_readlane_b32 s0, v252, 48
	v_readlane_b32 s1, v252, 49
	s_waitcnt lgkmcnt(0)
	v_mul_f32_e32 v8, 0x3fb8aa3b, v8
	v_exp_f32_e32 v8, v8
	v_lshl_add_u64 v[10:11], s[0:1], 0, v[10:11]
	global_store_dword v[10:11], v8, off
	s_branch .LBB0_537

; DEVI void mix_scan_phase(const MixArgs a, bool with_n) {
;     ...
;     if (with_n) for (int e = gt; e < 16 * 128; e += nthr) { const int dk = e & 127, bh = e >> 7; float run = 0.f;
;         for (int c = 0; c < NCH; ++c) { const size_t o = ((size_t)bh * NCH + c) * 128 + dk; const float x = a.dn[o], d = a.dec[o]; a.dn[o] = run; run = d * run + x; } }
.LBB0_632:
	v_lshl_add_u64 v[6:7], v[2:3], 0, s[6:7]
	v_add_co_u32_e32 v10, vcc, 0x1d580000, v6
	s_add_u32 s6, s6, 0x1000
	s_nop 0
	v_addc_co_u32_e32 v11, vcc, 0, v7, vcc
	v_add_co_u32_e32 v6, vcc, 0x1d600000, v6
	s_addc_u32 s7, s7, 0
	s_nop 0
	v_addc_co_u32_e32 v7, vcc, 0, v7, vcc
	global_load_dword v20, v[10:11], off
	global_load_dword v28, v[6:7], off
	global_load_dword v21, v[10:11], off offset:512
	global_load_dword v29, v[6:7], off offset:512
	global_load_dword v22, v[10:11], off offset:1024
	global_load_dword v30, v[6:7], off offset:1024
	global_load_dword v23, v[10:11], off offset:1536
	global_load_dword v31, v[6:7], off offset:1536
	global_load_dword v24, v[10:11], off offset:2048
	global_load_dword v32, v[6:7], off offset:2048
	global_load_dword v25, v[10:11], off offset:2560
	global_load_dword v33, v[6:7], off offset:2560
	global_load_dword v26, v[10:11], off offset:3072
	global_load_dword v34, v[6:7], off offset:3072
	global_load_dword v27, v[10:11], off offset:3584
	global_load_dword v35, v[6:7], off offset:3584
	global_store_dword v[10:11], v4, off
	s_waitcnt vmcnt(15)
	v_fmac_f32_e32 v20, v4, v28
	global_store_dword v[10:11], v20, off offset:512
	s_waitcnt vmcnt(14)
	v_fmac_f32_e32 v21, v20, v29
	global_store_dword v[10:11], v21, off offset:1024
	s_waitcnt vmcnt(13)
	v_fmac_f32_e32 v22, v21, v30
	global_store_dword v[10:11], v22, off offset:1536
	s_waitcnt vmcnt(12)
	v_fmac_f32_e32 v23, v22, v31
	global_store_dword v[10:11], v23, off offset:2048
	s_waitcnt vmcnt(11)
	v_fmac_f32_e32 v24, v23, v32
	global_store_dword v[10:11], v24, off offset:2560
	s_waitcnt vmcnt(10)
	v_fmac_f32_e32 v25, v24, v33
	global_store_dword v[10:11], v25, off offset:3072
	s_waitcnt vmcnt(9)
	v_fmac_f32_e32 v26, v25, v34
	global_store_dword v[10:11], v26, off offset:3584
	s_waitcnt vmcnt(8)
	v_fmac_f32_e32 v27, v26, v35
	v_mov_b32_e32 v4, v27
	s_cmpk_eq_u32 s6, 0x8000
	s_cbranch_scc0 .LBB0_632
	v_add_u32_e32 v16, s40, v16
	s_movk_i32 s0, 0x7ff
	v_cmp_lt_i32_e32 vcc, s0, v16
	s_or_b64 s[4:5], vcc, s[4:5]
	s_andn2_b64 exec, exec, s[4:5]
	s_cbranch_execnz .LBB0_631

; DEVI void lds_barrier() { asm volatile("s_waitcnt lgkmcnt(0)\n\ts_barrier" ::: "memory"); }
; template <int KIND>
; DEVI void mix_out_phase(unsigned char* smem, const MixArgs a) {
;     ...
;             for (int t = sg * 32; t < sg * 32 + 32; ++t) ssum += gla_la(gl, t, w2r, gb);
;             seg[sg * 128 + ch] = ssum; lds_barrier();
;             float Bc = 0.f;
; #pragma unroll
;             for (int s2 = 0; s2 < 4; ++s2) { const float v = seg[s2 * 128 + ch]; if (s2 < sg) Bc += v; }
.LBB0_691:
	v_add_u32_e32 v84, s0, v195
	ds_read_b128 v[68:71], v84
	ds_read_b128 v[72:75], v84 offset:16
	ds_read_b128 v[76:79], v84 offset:32
	ds_read_b128 v[80:83], v84 offset:48
	ds_read_b128 v[100:103], v84 offset:64
	ds_read_b128 v[104:107], v84 offset:80
	ds_read_b128 v[108:111], v84 offset:96
	ds_read_b128 v[112:115], v84 offset:112
	s_addk_i32 s0, 0x80
	s_waitcnt vmcnt(1) lgkmcnt(7)
	v_fma_f32 v85, v63, v68, v66
	v_fmac_f32_e32 v85, v64, v69
	v_fmac_f32_e32 v85, v60, v70
	v_fmac_f32_e32 v85, v65, v71
	s_waitcnt lgkmcnt(6)
	v_fmac_f32_e32 v85, v61, v72
	v_fmac_f32_e32 v85, v62, v73
	v_pk_mul_f32 v[68:69], v[34:35], v[74:75]
	s_cmpk_eq_i32 s0, 0x800
	v_add_f32_e32 v68, v85, v68
	v_add_f32_e32 v70, v68, v69
	s_waitcnt lgkmcnt(5)
	v_pk_mul_f32 v[68:69], v[36:37], v[76:77]
	s_nop 0
	v_add_f32_e32 v68, v70, v68
	v_add_f32_e32 v70, v68, v69
	v_pk_mul_f32 v[68:69], v[38:39], v[78:79]
	s_nop 0
	v_add_f32_e32 v68, v70, v68
	v_add_f32_e32 v70, v68, v69
	s_waitcnt lgkmcnt(4)
	v_pk_mul_f32 v[68:69], v[40:41], v[80:81]
	s_nop 0
	v_add_f32_e32 v68, v70, v68
	v_add_f32_e32 v70, v68, v69
	s_waitcnt vmcnt(0)
	v_pk_mul_f32 v[68:69], v[58:59], v[82:83]
	s_nop 0
	v_add_f32_e32 v68, v70, v68
	v_add_f32_e32 v68, v68, v69
	v_min_f32_e32 v69, 0, v68
	v_mul_f32_e64 v68, |v68|, s73
	v_exp_f32_e32 v68, v68
	s_nop 0
	v_add_f32_e32 v68, 1.0, v68
	v_cmp_gt_f32_e32 vcc, s94, v68
	s_nop 1
	v_cndmask_b32_e64 v70, 0, 32, vcc
	v_ldexp_f32 v68, v68, v70
	v_log_f32_e32 v68, v68
	s_nop 0
	v_mul_f32_e32 v70, 0x3f317217, v68
	v_fma_f32 v70, v68, s97, -v70
	v_fmac_f32_e32 v70, 0x3377d1cf, v68
	v_fmac_f32_e32 v70, 0x3f317217, v68
	v_cmp_lt_f32_e64 s[14:15], |v68|, s23
	s_nop 1
	v_cndmask_b32_e64 v68, v68, v70, s[14:15]
	v_cndmask_b32_e32 v70, 0, v211, vcc
	v_sub_f32_e32 v68, v68, v70
	v_sub_f32_e32 v68, v69, v68
	v_fmac_f32_e32 v67, 0x3d800000, v68
	s_waitcnt lgkmcnt(0)
	v_fma_f32 v72, v63, v100, v66
	v_fmac_f32_e32 v72, v64, v101
	v_fmac_f32_e32 v72, v60, v102
	v_fmac_f32_e32 v72, v65, v103
	v_fmac_f32_e32 v72, v61, v104
	v_fmac_f32_e32 v72, v62, v105
	v_pk_mul_f32 v[68:69], v[34:35], v[106:107]
	s_nop 0
	v_add_f32_e32 v68, v72, v68
	v_add_f32_e32 v72, v68, v69
	v_pk_mul_f32 v[68:69], v[36:37], v[108:109]
	s_nop 0
	v_add_f32_e32 v68, v72, v68
	v_add_f32_e32 v72, v68, v69
	v_pk_mul_f32 v[68:69], v[38:39], v[110:111]
	s_nop 0
	v_add_f32_e32 v68, v72, v68
	v_add_f32_e32 v72, v68, v69
	v_pk_mul_f32 v[68:69], v[40:41], v[112:113]
	s_nop 0
	v_add_f32_e32 v68, v72, v68
	v_add_f32_e32 v72, v68, v69
	v_pk_mul_f32 v[68:69], v[58:59], v[114:115]
	s_nop 0
	v_add_f32_e32 v68, v72, v68
	v_add_f32_e32 v68, v68, v69
	v_min_f32_e32 v69, 0, v68
	v_mul_f32_e64 v68, |v68|, s73
	v_exp_f32_e32 v68, v68
	s_nop 0
	v_add_f32_e32 v68, 1.0, v68
	v_cmp_gt_f32_e32 vcc, s94, v68
	s_nop 1
	v_cndmask_b32_e64 v70, 0, 32, vcc
	v_ldexp_f32 v68, v68, v70
	v_log_f32_e32 v68, v68
	s_nop 0
	v_mul_f32_e32 v70, 0x3f317217, v68
	v_fma_f32 v70, v68, s97, -v70
	v_fmac_f32_e32 v70, 0x3377d1cf, v68
	v_fmac_f32_e32 v70, 0x3f317217, v68
	v_cmp_lt_f32_e64 s[14:15], |v68|, s23
	s_nop 1
	v_cndmask_b32_e64 v68, v68, v70, s[14:15]
	v_cndmask_b32_e32 v70, 0, v211, vcc
	v_sub_f32_e32 v68, v68, v70
	v_sub_f32_e32 v68, v69, v68
	v_fmac_f32_e32 v67, 0x3d800000, v68
	s_cbranch_scc0 .LBB0_691
	ds_write_b32 v204, v67 offset:1536
	s_waitcnt lgkmcnt(0)
	s_barrier
	v_mov_b32_e32 v67, 0
	s_and_saveexec_b64 s[14:15], s[6:7]
	s_cbranch_execz .LBB0_696
	ds_read_b32 v67, v205 offset:1536
	s_waitcnt lgkmcnt(0)
	v_add_f32_e32 v67, 0, v67
	s_or_b64 exec, exec, s[14:15]
	s_and_saveexec_b64 s[14:15], s[8:9]
	s_cbranch_execnz .LBB0_697

; DEVI float bf2f(u16 b) { return __uint_as_float(((unsigned)b) << 16); }
; DEVI u16 f2bf(float f) { return (u16)(cvt_pk(f, 0.f) & 0xffffu); }
; DEVI void lds_barrier() { asm volatile("s_waitcnt lgkmcnt(0)\n\ts_barrier" ::: "memory"); }
; template <int KIND>
; DEVI void mix_out_phase(unsigned char* smem, const MixArgs a) {
;     ...
;             for (int t = sg * 32; t < sg * 32 + 32; ++t) { Bc += gla_la(gl, t, w2r, gb);
;                 QS[t * LP + ch] = f2bf(bf2f(QS[t * LP + ch]) * 0.08838834764831845f * __expf(Bc)); KS[t * LP + ch] = f2bf(bf2f(KS[t * LP + ch]) * __expf(-Bc)); }
;         }
;         lds_barrier();
;         bf16x8 qa[4];
; #pragma unroll
;         for (int ks = 0; ks < 4; ++ks) qa[ks] = *(const bf16x8*)(QS + trow * LP + ks * 32 + fq * 8);
.LBB0_701:
	v_add_u32_e32 v69, s0, v195
	ds_read_b128 v[70:73], v69
	ds_read_b128 v[74:77], v69 offset:16
	ds_read_b128 v[78:81], v69 offset:32
	ds_read_b128 v[82:85], v69 offset:48
	ds_read_b128 v[100:103], v69 offset:64
	ds_read_b128 v[104:107], v69 offset:80
	ds_read_b128 v[108:111], v69 offset:96
	ds_read_b128 v[112:115], v69 offset:112
	s_waitcnt lgkmcnt(7)
	v_fma_f32 v70, v63, v70, v66
	v_fmac_f32_e32 v70, v64, v71
	v_fmac_f32_e32 v70, v60, v72
	v_fmac_f32_e32 v70, v65, v73
	s_waitcnt lgkmcnt(6)
	v_fmac_f32_e32 v70, v61, v74
	v_fmac_f32_e32 v70, v62, v75
	v_fmac_f32_e32 v70, v34, v76
	v_fmac_f32_e32 v70, v35, v77
	s_waitcnt lgkmcnt(5)
	v_fmac_f32_e32 v70, v36, v78
	v_fmac_f32_e32 v70, v37, v79
	v_fmac_f32_e32 v70, v38, v80
	v_fmac_f32_e32 v70, v39, v81
	s_waitcnt lgkmcnt(4)
	v_fmac_f32_e32 v70, v40, v82
	v_fmac_f32_e32 v70, v41, v83
	v_fmac_f32_e32 v70, v58, v84
	v_fmac_f32_e32 v70, v59, v85
	v_min_f32_e32 v71, 0, v70
	v_mul_f32_e64 v70, |v70|, s73
	v_exp_f32_e32 v70, v70
	s_nop 0
	v_add_f32_e32 v70, 1.0, v70
	v_cmp_gt_f32_e32 vcc, s94, v70
	s_nop 1
	v_cndmask_b32_e64 v72, 0, 32, vcc
	v_ldexp_f32 v70, v70, v72
	v_log_f32_e32 v70, v70
	s_nop 0
	v_mul_f32_e32 v72, 0x3f317217, v70
	v_fma_f32 v72, v70, s97, -v72
	v_fmac_f32_e32 v72, 0x3377d1cf, v70
	v_fmac_f32_e32 v72, 0x3f317217, v70
	v_cmp_lt_f32_e64 s[14:15], |v70|, s23
	s_nop 1
	v_cndmask_b32_e64 v70, v70, v72, s[14:15]
	v_cndmask_b32_e32 v72, 0, v211, vcc
	v_sub_f32_e32 v70, v70, v72
	v_sub_f32_e32 v70, v71, v70
	v_fmac_f32_e32 v67, 0x3d800000, v70
	ds_read_u16 v70, v68
	v_mul_f32_e32 v71, 0x3fb8aa3b, v67
	v_exp_f32_e32 v71, v71
	s_waitcnt lgkmcnt(0)
	v_lshlrev_b32_e32 v70, 16, v70
	v_mul_f32_e32 v70, 0x3db504f3, v70
	v_mul_f32_e32 v70, v70, v71
	v_cvt_pk_bf16_f32 v70, v70, s0
	ds_write_b16 v68, v70
	ds_read_u16 v70, v68 offset:34816
	v_mul_f32_e32 v71, 0xbfb8aa3b, v67
	v_exp_f32_e32 v71, v71
	s_waitcnt lgkmcnt(0)
	v_lshlrev_b32_e32 v70, 16, v70
	v_mul_f32_e32 v70, v71, v70
	v_cvt_pk_bf16_f32 v70, v70, s0
	ds_write_b16 v68, v70 offset:34816
	s_waitcnt lgkmcnt(0)
	v_fma_f32 v74, v63, v100, v66
	v_fmac_f32_e32 v74, v64, v101
	v_fmac_f32_e32 v74, v60, v102
	v_fmac_f32_e32 v74, v65, v103
	v_fmac_f32_e32 v74, v61, v104
	v_fmac_f32_e32 v74, v62, v105
	v_fmac_f32_e32 v74, v34, v106
	v_fmac_f32_e32 v74, v35, v107
	v_fmac_f32_e32 v74, v36, v108
	v_fmac_f32_e32 v74, v37, v109
	v_fmac_f32_e32 v74, v38, v110
	v_fmac_f32_e32 v74, v39, v111
	v_fmac_f32_e32 v74, v40, v112
	v_fmac_f32_e32 v74, v41, v113
	v_fmac_f32_e32 v74, v58, v114
	v_fmac_f32_e32 v74, v59, v115
	v_mul_f32_e64 v70, |v74|, s73
	v_exp_f32_e32 v70, v70
	v_min_f32_e32 v69, 0, v74
	v_add_f32_e32 v70, 1.0, v70
	v_cmp_gt_f32_e32 vcc, s94, v70
	s_nop 1
	v_cndmask_b32_e64 v71, 0, 32, vcc
	v_ldexp_f32 v70, v70, v71
	v_log_f32_e32 v70, v70
	s_nop 0
	v_mul_f32_e32 v71, 0x3f317217, v70
	v_fma_f32 v71, v70, s97, -v71
	v_fmac_f32_e32 v71, 0x3377d1cf, v70
	v_fmac_f32_e32 v71, 0x3f317217, v70
	v_cmp_lt_f32_e64 s[14:15], |v70|, s23
	s_nop 1
	v_cndmask_b32_e64 v70, v70, v71, s[14:15]
	v_cndmask_b32_e32 v71, 0, v211, vcc
	v_sub_f32_e32 v70, v70, v71
	v_sub_f32_e32 v69, v69, v70
	v_fmac_f32_e32 v67, 0x3d800000, v69
	ds_read_u16 v69, v68 offset:272
	v_mul_f32_e32 v70, 0x3fb8aa3b, v67
	v_exp_f32_e32 v70, v70
	s_waitcnt lgkmcnt(0)
	v_lshlrev_b32_e32 v69, 16, v69
	v_mul_f32_e32 v69, 0x3db504f3, v69
	v_mul_f32_e32 v69, v69, v70
	v_cvt_pk_bf16_f32 v69, v69, s0
	ds_write_b16 v68, v69 offset:272
	ds_read_u16 v69, v68 offset:35088
	v_mul_f32_e32 v70, 0xbfb8aa3b, v67
	v_exp_f32_e32 v70, v70
	s_waitcnt lgkmcnt(0)
	v_lshlrev_b32_e32 v69, 16, v69
	v_mul_f32_e32 v69, v70, v69
	v_cvt_pk_bf16_f32 v69, v69, s0
	s_addk_i32 s0, 0x80
	ds_write_b16 v68, v69 offset:35088
	v_add_u32_e32 v68, 0x220, v68
	s_cmpk_eq_i32 s0, 0x800
	s_cbranch_scc0 .LBB0_701
	s_waitcnt lgkmcnt(0)
	s_barrier
	ds_read_b128 v[94:97], v225 offset:16384
	ds_read_b128 v[90:93], v225 offset:16448
	ds_read_b128 v[86:89], v225 offset:16512
	ds_read_b128 v[82:85], v225 offset:16576
	s_and_saveexec_b64 s[14:15], s[2:3]
	s_cbranch_execz .LBB0_707
	s_mov_b32 s0, 0
	s_mov_b64 s[82:83], 0
	v_mov_b32_e32 v34, v218
	v_mov_b32_e32 v35, v216
	v_mov_b32_e32 v36, v206
	s_branch .LBB0_705
